# adds: s_setprio flips removed from the GLA-out GEMM K-loop as well (all five GEMM loops now without priority flips)
# speedup vs baseline: 1.0118x; 1.0002x over previous
; #define PG8_STAGE(bufoff, gbase, voff) do { _Pragma("unroll") for (int _i = 0; _i < 2; ++_i) \
;         __builtin_amdgcn_global_load_lds((const unsigned*)((const char*)(gbase) + (voff)[_i]), (LAS unsigned*)(lds + (bufoff) + ldsw + _i * 8192), 16, 0, 0); } while (0)
; #define PG8_LDA(dst, b, h) do { _Pragma("unroll") for (int m = 0; m < 4; ++m) _Pragma("unroll") for (int k = 0; k < 2; ++k) dst[m][k] = *(const LAS bf16x8*)(lds + PG8_SA(b, h) + aoff + m * 2048 + k * 1024); } while (0)
; #define PG8_LDB(dst, b, h) do { _Pragma("unroll") for (int n = 0; n < 2; ++n) _Pragma("unroll") for (int k = 0; k < 2; ++k) dst[n][k] = *(const LAS bf16x8*)(lds + PG8_SB(b, h) + boff + n * 2048 + k * 1024); } while (0)
; #define PG8_MMA(ai, bj, At, Bt) do { __builtin_amdgcn_s_setprio(1); _Pragma("unroll") for (int m = 0; m < 4; ++m) _Pragma("unroll") for (int n = 0; n < 2; ++n) _Pragma("unroll") for (int k = 0; k < 2; ++k) \
;         acc[ai][bj][m][n] = __builtin_amdgcn_mfma_f32_16x16x32_bf16(Bt[n][k], At[m][k], acc[ai][bj][m][n], 0, 0, 0); __builtin_amdgcn_s_setprio(0); } while (0)
; #define PG8_BAR __builtin_amdgcn_s_barrier()
; template <class Epi, class Sched>
; __device__ __forceinline__ void gemm_phase(LAS unsigned char* lds, const Gemm g, const Sched& S, const Epi& E) {
;     ...
;         const bool has_next = S.next(ui + 1, nxt);
;         const char* nA = has_next ? (const char*)g.A + (size_t)nxt.pm * tstepA + (size_t)nxt.pn * apn : cA; const char* nB = has_next ? (const char*)g.Bt + (size_t)nxt.pn * tstepB : cB;
;         for (int t = 0; t < nt; t += 2) {
;             const bool last = (t == nt - 2);
;             const char* a1 = cA + (size_t)(t + 1) * kstep;
;             const char* a2 = last ? nA : cA + (size_t)(t + 2) * kstep; const char* b2 = last ? nB : cB + (size_t)(t + 2) * kstep;
;             const char* a3 = a2 + kstep; const char* b3 = b2 + kstep;
;             PG8_LDB(B0, 0, 0); PG8_LDB(B1, 0, 1); PG8_SCHED; PG8_LDA(At, 0, 0); PG8_STAGE(PG8_SA(1, 1), a1 + hstepA, voffA);
;             PG8_WAIT_V(8); PG8_WAIT_L(0); PG8_BAR; PG8_MMA(0, 0, At, B0); PG8_MMA(0, 1, At, B1); PG8_BAR; PG8_SCHED;
;             PG8_LDA(At, 0, 1); PG8_STAGE(PG8_SB(0, 0), b2, voffB); PG8_STAGE(PG8_SB(0, 1), b2 + hstepB, voffB); PG8_STAGE(PG8_SA(0, 0), a2, voffA);
;             PG8_WAIT_V(8); PG8_WAIT_L(0); PG8_BAR; PG8_MMA(1, 0, At, B0); PG8_MMA(1, 1, At, B1); PG8_BAR; PG8_SCHED;
.LBB0_628:
	s_add_u32 s0, s52, s6
	s_addc_u32 s23, s53, 0
	s_add_u32 s7, s0, 0x100
	s_addc_u32 s26, s23, 0
	s_and_b64 s[14:15], s[56:57], exec
	s_cselect_b32 vcc_hi, s45, s26
	s_cselect_b32 vcc_lo, s44, s7
	s_add_u32 s6, s50, s6
	s_addc_u32 s7, s51, 0
	s_add_u32 s14, s6, 0x100
	s_addc_u32 s15, s7, 0
	s_add_i32 s80, 0, 0x10000
	s_and_b64 s[6:7], s[56:57], exec
	s_cselect_b32 s7, s9, s15
	s_cselect_b32 s6, s13, s14
	s_add_i32 s57, 0, 0x14000
	s_add_u32 s78, s0, 0x40080
	s_addc_u32 s79, s23, 0
	s_add_i32 s97, s80, s24
	s_add_i32 m0, s25, 0xc000
	s_add_i32 s81, s25, 0xe000
	s_add_i32 s88, s97, 0x2000
	s_add_u32 s14, s6, 0x10000
	v_add_u32_e32 v140, s80, v174
	v_add_u32_e32 v164, s57, v174
	s_addc_u32 s15, s7, 0
	s_add_i32 s89, s57, s24
	ds_read_b128 v[128:131], v140
	ds_read_b128 v[132:135], v140 offset:1024
	ds_read_b128 v[136:139], v140 offset:2048
	ds_read_b128 v[140:143], v140 offset:3072
	ds_read_b128 v[144:147], v164
	ds_read_b128 v[148:151], v164 offset:1024
	ds_read_b128 v[152:155], v164 offset:2048
	ds_read_b128 v[164:167], v164 offset:3072
	s_add_i32 s96, s89, 0x2000
	s_add_i32 s35, 0, 0x18000
	s_add_i32 s0, 0, 0x1c000
	s_add_u32 s68, vcc_lo, 0x40000
	s_addc_u32 s69, vcc_hi, 0
	s_add_i32 s23, s35, s24
	s_add_i32 s26, s23, 0x2000
	s_add_u32 s56, s6, 0x10080
	s_addc_u32 s57, s7, 0
	s_add_i32 s83, s0, s24
	s_add_i32 s80, s83, 0x2000
	v_lshl_add_u64 v[192:193], s[78:79], 0, v[156:157]
	ds_read_b128 v[168:171], v191
	ds_read_b128 v[196:199], v191 offset:1024
	ds_read_b128 v[200:203], v191 offset:2048
	ds_read_b128 v[204:207], v191 offset:3072
	ds_read_b128 v[208:211], v191 offset:4096
	ds_read_b128 v[212:215], v191 offset:5120
	ds_read_b128 v[216:219], v191 offset:6144
	ds_read_b128 v[220:223], v191 offset:7168
	global_load_lds_dwordx4 v[192:193], off
	v_lshl_add_u64 v[192:193], s[78:79], 0, v[158:159]
	s_mov_b32 m0, s81
	s_nop 0
	global_load_lds_dwordx4 v[192:193], off
	s_waitcnt vmcnt(8)
	s_waitcnt lgkmcnt(0)
	s_barrier
	s_waitcnt lgkmcnt(0)
	v_mfma_f32_16x16x32_bf16 v[124:127], v[128:131], v[168:171], v[124:127]
	v_mfma_f32_16x16x32_bf16 v[120:123], v[136:139], v[168:171], v[120:123]
	v_mfma_f32_16x16x32_bf16 v[108:111], v[128:131], v[200:203], v[108:111]
	v_mfma_f32_16x16x32_bf16 v[104:107], v[136:139], v[200:203], v[104:107]
	v_mfma_f32_16x16x32_bf16 v[92:95], v[128:131], v[208:211], v[92:95]
	v_mfma_f32_16x16x32_bf16 v[88:91], v[136:139], v[208:211], v[88:91]
	v_mfma_f32_16x16x32_bf16 v[76:79], v[128:131], v[216:219], v[76:79]
	v_mfma_f32_16x16x32_bf16 v[72:75], v[136:139], v[216:219], v[72:75]
	v_mfma_f32_16x16x32_bf16 v[124:127], v[132:135], v[196:199], v[124:127]
	v_mfma_f32_16x16x32_bf16 v[120:123], v[140:143], v[196:199], v[120:123]
	v_mfma_f32_16x16x32_bf16 v[108:111], v[132:135], v[204:207], v[108:111]
	v_mfma_f32_16x16x32_bf16 v[104:107], v[140:143], v[204:207], v[104:107]
	v_mfma_f32_16x16x32_bf16 v[92:95], v[132:135], v[212:215], v[92:95]
	v_mfma_f32_16x16x32_bf16 v[88:91], v[140:143], v[212:215], v[88:91]
	v_mfma_f32_16x16x32_bf16 v[76:79], v[132:135], v[220:223], v[76:79]
	v_mfma_f32_16x16x32_bf16 v[72:75], v[140:143], v[220:223], v[72:75]
	v_mfma_f32_16x16x32_bf16 v[116:119], v[144:147], v[168:171], v[116:119]
	v_mfma_f32_16x16x32_bf16 v[112:115], v[152:155], v[168:171], v[112:115]
	v_mfma_f32_16x16x32_bf16 v[100:103], v[144:147], v[200:203], v[100:103]
	v_mfma_f32_16x16x32_bf16 v[96:99], v[152:155], v[200:203], v[96:99]
	v_mfma_f32_16x16x32_bf16 v[84:87], v[144:147], v[208:211], v[84:87]
	v_mfma_f32_16x16x32_bf16 v[80:83], v[152:155], v[208:211], v[80:83]
	v_mfma_f32_16x16x32_bf16 v[68:71], v[144:147], v[216:219], v[68:71]
	v_mfma_f32_16x16x32_bf16 v[64:67], v[152:155], v[216:219], v[64:67]
	v_mfma_f32_16x16x32_bf16 v[116:119], v[148:151], v[196:199], v[116:119]
	v_mfma_f32_16x16x32_bf16 v[112:115], v[164:167], v[196:199], v[112:115]
	v_mfma_f32_16x16x32_bf16 v[100:103], v[148:151], v[204:207], v[100:103]
	v_mfma_f32_16x16x32_bf16 v[96:99], v[164:167], v[204:207], v[96:99]
	v_mfma_f32_16x16x32_bf16 v[84:87], v[148:151], v[212:215], v[84:87]
	v_mfma_f32_16x16x32_bf16 v[80:83], v[164:167], v[212:215], v[80:83]
	v_mfma_f32_16x16x32_bf16 v[68:71], v[148:151], v[220:223], v[68:71]
	v_mfma_f32_16x16x32_bf16 v[64:67], v[164:167], v[220:223], v[64:67]
	s_barrier
	s_mov_b32 m0, s97
	v_lshl_add_u64 v[192:193], s[6:7], 0, v[160:161]
	ds_read_b128 v[168:171], v191 offset:16384
	ds_read_b128 v[196:199], v191 offset:17408
	ds_read_b128 v[200:203], v191 offset:18432
	ds_read_b128 v[204:207], v191 offset:19456
	ds_read_b128 v[208:211], v191 offset:20480
	ds_read_b128 v[212:215], v191 offset:21504
	ds_read_b128 v[216:219], v191 offset:22528
	ds_read_b128 v[220:223], v191 offset:23552
	global_load_lds_dwordx4 v[192:193], off
	v_lshl_add_u64 v[224:225], s[6:7], 0, v[162:163]
	s_mov_b32 m0, s88
	v_lshl_add_u64 v[226:227], s[14:15], 0, v[160:161]
	global_load_lds_dwordx4 v[224:225], off
	s_mov_b32 m0, s89
	v_lshl_add_u64 v[228:229], vcc, 0, v[158:159]
	global_load_lds_dwordx4 v[226:227], off
	v_lshl_add_u64 v[226:227], s[14:15], 0, v[162:163]
	s_mov_b32 m0, s96
	s_nop 0
	global_load_lds_dwordx4 v[226:227], off
	v_lshl_add_u64 v[226:227], vcc, 0, v[156:157]
	s_mov_b32 m0, s25
	s_nop 0
	global_load_lds_dwordx4 v[226:227], off
	s_mov_b32 m0, s49
	s_nop 0
	global_load_lds_dwordx4 v[228:229], off
	s_waitcnt vmcnt(8)
	s_waitcnt lgkmcnt(0)
	s_barrier
; #define PG8_STAGE(bufoff, gbase, voff) do { _Pragma("unroll") for (int _i = 0; _i < 2; ++_i) \
;         __builtin_amdgcn_global_load_lds((const unsigned*)((const char*)(gbase) + (voff)[_i]), (LAS unsigned*)(lds + (bufoff) + ldsw + _i * 8192), 16, 0, 0); } while (0)
; #define PG8_LDA(dst, b, h) do { _Pragma("unroll") for (int m = 0; m < 4; ++m) _Pragma("unroll") for (int k = 0; k < 2; ++k) dst[m][k] = *(const LAS bf16x8*)(lds + PG8_SA(b, h) + aoff + m * 2048 + k * 1024); } while (0)
; #define PG8_LDB(dst, b, h) do { _Pragma("unroll") for (int n = 0; n < 2; ++n) _Pragma("unroll") for (int k = 0; k < 2; ++k) dst[n][k] = *(const LAS bf16x8*)(lds + PG8_SB(b, h) + boff + n * 2048 + k * 1024); } while (0)
; #define PG8_MMA(ai, bj, At, Bt) do { __builtin_amdgcn_s_setprio(1); _Pragma("unroll") for (int m = 0; m < 4; ++m) _Pragma("unroll") for (int n = 0; n < 2; ++n) _Pragma("unroll") for (int k = 0; k < 2; ++k) \
;         acc[ai][bj][m][n] = __builtin_amdgcn_mfma_f32_16x16x32_bf16(Bt[n][k], At[m][k], acc[ai][bj][m][n], 0, 0, 0); __builtin_amdgcn_s_setprio(0); } while (0)
; #define PG8_WAIT_V(n) asm volatile("s_waitcnt vmcnt(" #n ")" ::: "memory")
; #define PG8_WAIT_L(n) asm volatile("s_waitcnt lgkmcnt(" #n ")" ::: "memory")
; #define PG8_BAR __builtin_amdgcn_s_barrier()
; #define PG8_SCHED __builtin_amdgcn_sched_barrier(0)
; template <class Epi, class Sched>
; __device__ __forceinline__ void gemm_phase(LAS unsigned char* lds, const Gemm g, const Sched& S, const Epi& E) {
;     ...
;             PG8_WAIT_V(8); PG8_WAIT_L(0); PG8_BAR; PG8_MMA(1, 0, At, B0); PG8_MMA(1, 1, At, B1); PG8_BAR; PG8_SCHED;
;             PG8_LDB(B0, 1, 0); PG8_LDB(B1, 1, 1); PG8_SCHED; PG8_LDA(At, 1, 0); PG8_STAGE(PG8_SA(0, 1), a2 + hstepA, voffA);
;             PG8_WAIT_V(8); PG8_WAIT_L(0); PG8_BAR; PG8_MMA(0, 0, At, B0); PG8_MMA(0, 1, At, B1); PG8_BAR; PG8_SCHED;
	s_waitcnt lgkmcnt(0)
	v_mfma_f32_16x16x32_bf16 v[60:63], v[128:131], v[168:171], v[60:63]
	v_mfma_f32_16x16x32_bf16 v[56:59], v[136:139], v[168:171], v[56:59]
	v_mfma_f32_16x16x32_bf16 v[44:47], v[128:131], v[200:203], v[44:47]
	v_mfma_f32_16x16x32_bf16 v[40:43], v[136:139], v[200:203], v[40:43]
	v_mfma_f32_16x16x32_bf16 v[28:31], v[128:131], v[208:211], v[28:31]
	v_mfma_f32_16x16x32_bf16 v[24:27], v[136:139], v[208:211], v[24:27]
	v_mfma_f32_16x16x32_bf16 v[12:15], v[128:131], v[216:219], v[12:15]
	v_mfma_f32_16x16x32_bf16 v[8:11], v[136:139], v[216:219], v[8:11]
	v_mfma_f32_16x16x32_bf16 v[60:63], v[132:135], v[196:199], v[60:63]
	v_mfma_f32_16x16x32_bf16 v[56:59], v[140:143], v[196:199], v[56:59]
	v_mfma_f32_16x16x32_bf16 v[44:47], v[132:135], v[204:207], v[44:47]
	v_mfma_f32_16x16x32_bf16 v[40:43], v[140:143], v[204:207], v[40:43]
	v_mfma_f32_16x16x32_bf16 v[28:31], v[132:135], v[212:215], v[28:31]
	v_mfma_f32_16x16x32_bf16 v[24:27], v[140:143], v[212:215], v[24:27]
	v_mfma_f32_16x16x32_bf16 v[12:15], v[132:135], v[220:223], v[12:15]
	v_mfma_f32_16x16x32_bf16 v[8:11], v[140:143], v[220:223], v[8:11]
	v_mfma_f32_16x16x32_bf16 v[52:55], v[144:147], v[168:171], v[52:55]
	v_mfma_f32_16x16x32_bf16 v[48:51], v[152:155], v[168:171], v[48:51]
	v_mfma_f32_16x16x32_bf16 v[36:39], v[144:147], v[200:203], v[36:39]
	v_mfma_f32_16x16x32_bf16 v[32:35], v[152:155], v[200:203], v[32:35]
	v_mfma_f32_16x16x32_bf16 v[20:23], v[144:147], v[208:211], v[20:23]
	v_mfma_f32_16x16x32_bf16 v[16:19], v[152:155], v[208:211], v[16:19]
	v_mfma_f32_16x16x32_bf16 v[4:7], v[144:147], v[216:219], v[4:7]
	v_mfma_f32_16x16x32_bf16 v[0:3], v[152:155], v[216:219], v[0:3]
	v_mfma_f32_16x16x32_bf16 v[52:55], v[148:151], v[196:199], v[52:55]
	v_mfma_f32_16x16x32_bf16 v[48:51], v[164:167], v[196:199], v[48:51]
	v_mfma_f32_16x16x32_bf16 v[36:39], v[148:151], v[204:207], v[36:39]
	v_mfma_f32_16x16x32_bf16 v[32:35], v[164:167], v[204:207], v[32:35]
	v_mfma_f32_16x16x32_bf16 v[20:23], v[148:151], v[212:215], v[20:23]
	v_mfma_f32_16x16x32_bf16 v[16:19], v[164:167], v[212:215], v[16:19]
	v_mfma_f32_16x16x32_bf16 v[4:7], v[148:151], v[220:223], v[4:7]
	v_mfma_f32_16x16x32_bf16 v[0:3], v[164:167], v[220:223], v[0:3]
	s_barrier
	v_add_u32_e32 v140, s35, v174
	v_add_u32_e32 v164, s0, v174
	ds_read_b128 v[128:131], v140
	ds_read_b128 v[132:135], v140 offset:1024
	ds_read_b128 v[136:139], v140 offset:2048
	ds_read_b128 v[140:143], v140 offset:3072
	ds_read_b128 v[144:147], v164
	ds_read_b128 v[148:151], v164 offset:1024
	ds_read_b128 v[152:155], v164 offset:2048
	ds_read_b128 v[164:167], v164 offset:3072
	s_mov_b32 m0, s82
	v_lshl_add_u64 v[230:231], s[68:69], 0, v[156:157]
	ds_read_b128 v[168:171], v191 offset:32768
	ds_read_b128 v[196:199], v191 offset:33792
	ds_read_b128 v[200:203], v191 offset:34816
	ds_read_b128 v[204:207], v191 offset:35840
	ds_read_b128 v[208:211], v191 offset:36864
	ds_read_b128 v[212:215], v191 offset:37888
	ds_read_b128 v[216:219], v191 offset:38912
	ds_read_b128 v[220:223], v191 offset:39936
	global_load_lds_dwordx4 v[230:231], off
	v_lshl_add_u64 v[230:231], s[68:69], 0, v[158:159]
	s_mov_b32 m0, s33
	s_nop 0
	global_load_lds_dwordx4 v[230:231], off
	s_waitcnt vmcnt(8)
	s_waitcnt lgkmcnt(0)
	s_barrier
	s_waitcnt lgkmcnt(0)
	v_mfma_f32_16x16x32_bf16 v[124:127], v[128:131], v[168:171], v[124:127]
	v_mfma_f32_16x16x32_bf16 v[120:123], v[136:139], v[168:171], v[120:123]
	v_mfma_f32_16x16x32_bf16 v[108:111], v[128:131], v[200:203], v[108:111]
	v_mfma_f32_16x16x32_bf16 v[104:107], v[136:139], v[200:203], v[104:107]
	v_mfma_f32_16x16x32_bf16 v[92:95], v[128:131], v[208:211], v[92:95]
	v_mfma_f32_16x16x32_bf16 v[88:91], v[136:139], v[208:211], v[88:91]
	v_mfma_f32_16x16x32_bf16 v[76:79], v[128:131], v[216:219], v[76:79]
	v_mfma_f32_16x16x32_bf16 v[72:75], v[136:139], v[216:219], v[72:75]
	v_mfma_f32_16x16x32_bf16 v[124:127], v[132:135], v[196:199], v[124:127]
	v_mfma_f32_16x16x32_bf16 v[120:123], v[140:143], v[196:199], v[120:123]
	v_mfma_f32_16x16x32_bf16 v[108:111], v[132:135], v[204:207], v[108:111]
	v_mfma_f32_16x16x32_bf16 v[104:107], v[140:143], v[204:207], v[104:107]
	v_mfma_f32_16x16x32_bf16 v[92:95], v[132:135], v[212:215], v[92:95]
	v_mfma_f32_16x16x32_bf16 v[88:91], v[140:143], v[212:215], v[88:91]
	v_mfma_f32_16x16x32_bf16 v[76:79], v[132:135], v[220:223], v[76:79]
	v_mfma_f32_16x16x32_bf16 v[72:75], v[140:143], v[220:223], v[72:75]
	v_mfma_f32_16x16x32_bf16 v[116:119], v[144:147], v[168:171], v[116:119]
	v_mfma_f32_16x16x32_bf16 v[112:115], v[152:155], v[168:171], v[112:115]
	v_mfma_f32_16x16x32_bf16 v[100:103], v[144:147], v[200:203], v[100:103]
	v_mfma_f32_16x16x32_bf16 v[96:99], v[152:155], v[200:203], v[96:99]
	v_mfma_f32_16x16x32_bf16 v[84:87], v[144:147], v[208:211], v[84:87]
	v_mfma_f32_16x16x32_bf16 v[80:83], v[152:155], v[208:211], v[80:83]
	v_mfma_f32_16x16x32_bf16 v[68:71], v[144:147], v[216:219], v[68:71]
	v_mfma_f32_16x16x32_bf16 v[64:67], v[152:155], v[216:219], v[64:67]
	v_mfma_f32_16x16x32_bf16 v[116:119], v[148:151], v[196:199], v[116:119]
	v_mfma_f32_16x16x32_bf16 v[112:115], v[164:167], v[196:199], v[112:115]
	v_mfma_f32_16x16x32_bf16 v[100:103], v[148:151], v[204:207], v[100:103]
	v_mfma_f32_16x16x32_bf16 v[96:99], v[164:167], v[204:207], v[96:99]
	v_mfma_f32_16x16x32_bf16 v[84:87], v[148:151], v[212:215], v[84:87]
	v_mfma_f32_16x16x32_bf16 v[80:83], v[164:167], v[212:215], v[80:83]
	v_mfma_f32_16x16x32_bf16 v[68:71], v[148:151], v[220:223], v[68:71]
	v_mfma_f32_16x16x32_bf16 v[64:67], v[164:167], v[220:223], v[64:67]
	s_barrier
; #define PG8_STAGE(bufoff, gbase, voff) do { _Pragma("unroll") for (int _i = 0; _i < 2; ++_i) \
;         __builtin_amdgcn_global_load_lds((const unsigned*)((const char*)(gbase) + (voff)[_i]), (LAS unsigned*)(lds + (bufoff) + ldsw + _i * 8192), 16, 0, 0); } while (0)
; #define PG8_LDA(dst, b, h) do { _Pragma("unroll") for (int m = 0; m < 4; ++m) _Pragma("unroll") for (int k = 0; k < 2; ++k) dst[m][k] = *(const LAS bf16x8*)(lds + PG8_SA(b, h) + aoff + m * 2048 + k * 1024); } while (0)
; #define PG8_MMA(ai, bj, At, Bt) do { __builtin_amdgcn_s_setprio(1); _Pragma("unroll") for (int m = 0; m < 4; ++m) _Pragma("unroll") for (int n = 0; n < 2; ++n) _Pragma("unroll") for (int k = 0; k < 2; ++k) \
;         acc[ai][bj][m][n] = __builtin_amdgcn_mfma_f32_16x16x32_bf16(Bt[n][k], At[m][k], acc[ai][bj][m][n], 0, 0, 0); __builtin_amdgcn_s_setprio(0); } while (0)
; #define PG8_WAIT_V(n) asm volatile("s_waitcnt vmcnt(" #n ")" ::: "memory")
; #define PG8_WAIT_L(n) asm volatile("s_waitcnt lgkmcnt(" #n ")" ::: "memory")
; #define PG8_BAR __builtin_amdgcn_s_barrier()
; #define PG8_SCHED __builtin_amdgcn_sched_barrier(0)
; template <class Epi, class Sched>
; __device__ __forceinline__ void gemm_phase(LAS unsigned char* lds, const Gemm g, const Sched& S, const Epi& E) {
;     ...
;             PG8_LDA(At, 1, 1); PG8_STAGE(PG8_SB(1, 0), b3, voffB); PG8_STAGE(PG8_SB(1, 1), b3 + hstepB, voffB); PG8_STAGE(PG8_SA(1, 0), a3, voffA);
;             PG8_WAIT_V(8); PG8_WAIT_L(0); PG8_BAR; PG8_MMA(1, 0, At, B0); PG8_MMA(1, 1, At, B1); PG8_BAR; PG8_SCHED;
;         }
;         if (wr == 0) PG8_BAR;
	s_mov_b32 m0, s23
	v_lshl_add_u64 v[192:193], v[192:193], 0, s[30:31]
	ds_read_b128 v[168:171], v191 offset:49152
	ds_read_b128 v[196:199], v191 offset:50176
	ds_read_b128 v[200:203], v191 offset:51200
	ds_read_b128 v[204:207], v191 offset:52224
	ds_read_b128 v[208:211], v191 offset:53248
	ds_read_b128 v[212:215], v191 offset:54272
	ds_read_b128 v[216:219], v191 offset:55296
	ds_read_b128 v[220:223], v191 offset:56320
	global_load_lds_dwordx4 v[192:193], off
	v_lshl_add_u64 v[192:193], v[224:225], 0, s[30:31]
	s_mov_b32 m0, s26
	s_nop 0
	global_load_lds_dwordx4 v[192:193], off
	v_lshl_add_u64 v[192:193], s[56:57], 0, v[160:161]
	s_mov_b32 m0, s83
	s_nop 0
	global_load_lds_dwordx4 v[192:193], off
	v_lshl_add_u64 v[192:193], s[56:57], 0, v[162:163]
	s_mov_b32 m0, s80
	s_nop 0
	global_load_lds_dwordx4 v[192:193], off
	v_lshl_add_u64 v[192:193], v[226:227], 0, s[30:31]
	s_mov_b32 m0, s90
	s_nop 0
	global_load_lds_dwordx4 v[192:193], off
	v_lshl_add_u64 v[192:193], v[228:229], 0, s[30:31]
	s_mov_b32 m0, s21
	s_nop 0
	global_load_lds_dwordx4 v[192:193], off
	s_waitcnt vmcnt(8)
	s_waitcnt lgkmcnt(0)
	s_barrier
	s_waitcnt lgkmcnt(0)
	v_mfma_f32_16x16x32_bf16 v[60:63], v[128:131], v[168:171], v[60:63]
	v_mfma_f32_16x16x32_bf16 v[56:59], v[136:139], v[168:171], v[56:59]
	v_mfma_f32_16x16x32_bf16 v[44:47], v[128:131], v[200:203], v[44:47]
	v_mfma_f32_16x16x32_bf16 v[40:43], v[136:139], v[200:203], v[40:43]
	v_mfma_f32_16x16x32_bf16 v[28:31], v[128:131], v[208:211], v[28:31]
	v_mfma_f32_16x16x32_bf16 v[24:27], v[136:139], v[208:211], v[24:27]
	v_mfma_f32_16x16x32_bf16 v[12:15], v[128:131], v[216:219], v[12:15]
	v_mfma_f32_16x16x32_bf16 v[8:11], v[136:139], v[216:219], v[8:11]
	v_mfma_f32_16x16x32_bf16 v[60:63], v[132:135], v[196:199], v[60:63]
	v_mfma_f32_16x16x32_bf16 v[56:59], v[140:143], v[196:199], v[56:59]
	v_mfma_f32_16x16x32_bf16 v[44:47], v[132:135], v[204:207], v[44:47]
	v_mfma_f32_16x16x32_bf16 v[40:43], v[140:143], v[204:207], v[40:43]
	v_mfma_f32_16x16x32_bf16 v[28:31], v[132:135], v[212:215], v[28:31]
	v_mfma_f32_16x16x32_bf16 v[24:27], v[140:143], v[212:215], v[24:27]
	v_mfma_f32_16x16x32_bf16 v[12:15], v[132:135], v[220:223], v[12:15]
	v_mfma_f32_16x16x32_bf16 v[8:11], v[140:143], v[220:223], v[8:11]
	v_mfma_f32_16x16x32_bf16 v[52:55], v[144:147], v[168:171], v[52:55]
	v_mfma_f32_16x16x32_bf16 v[48:51], v[152:155], v[168:171], v[48:51]
	v_mfma_f32_16x16x32_bf16 v[36:39], v[144:147], v[200:203], v[36:39]
	v_mfma_f32_16x16x32_bf16 v[32:35], v[152:155], v[200:203], v[32:35]
	v_mfma_f32_16x16x32_bf16 v[20:23], v[144:147], v[208:211], v[20:23]
	v_mfma_f32_16x16x32_bf16 v[16:19], v[152:155], v[208:211], v[16:19]
	v_mfma_f32_16x16x32_bf16 v[4:7], v[144:147], v[216:219], v[4:7]
	v_mfma_f32_16x16x32_bf16 v[0:3], v[152:155], v[216:219], v[0:3]
	v_mfma_f32_16x16x32_bf16 v[52:55], v[148:151], v[196:199], v[52:55]
	v_mfma_f32_16x16x32_bf16 v[48:51], v[164:167], v[196:199], v[48:51]
	v_mfma_f32_16x16x32_bf16 v[36:39], v[148:151], v[204:207], v[36:39]
	v_mfma_f32_16x16x32_bf16 v[32:35], v[164:167], v[204:207], v[32:35]
	v_mfma_f32_16x16x32_bf16 v[20:23], v[148:151], v[212:215], v[20:23]
	v_mfma_f32_16x16x32_bf16 v[16:19], v[164:167], v[212:215], v[16:19]
	v_mfma_f32_16x16x32_bf16 v[4:7], v[148:151], v[220:223], v[4:7]
	v_mfma_f32_16x16x32_bf16 v[0:3], v[164:167], v[220:223], v[0:3]
	s_barrier
	s_movk_i32 s6, 0x100
	s_andn2_b64 vcc, exec, s[54:55]
	s_mov_b64 s[56:57], -1
	s_mov_b64 s[54:55], 0
	s_cbranch_vccz .LBB0_628
	s_and_b64 vcc, exec, s[18:19]
	s_cbranch_vccz .LBB0_631
	s_barrier
